# attention loop: K-tile LDS stores of each half-step issued before the first barrier (only the V-tile stores remain between the barriers)
# speedup vs baseline: 1.0057x; 1.0057x over previous
.LBB0_217:
	v_mfma_f32_32x32x16_bf16 v[32:47], v[100:103], v[112:115], v[32:47]
	v_max_f32_e32 v252, v85, v85
	v_max_f32_e32 v253, v84, v84
	v_max_f32_e32 v252, v253, v252
	v_max3_f32 v252, v252, v86, v87
	v_max3_f32 v252, v252, v88, v89
	ds_read_b64_tr_b16 v[112:113], v211 offset:0x200
	ds_read_b64_tr_b16 v[114:115], v211 offset:0xa00
	v_mfma_f32_32x32x16_bf16 v[32:47], v[64:67], v[116:119], v[32:47]
	v_max3_f32 v252, v252, v90, v91
	v_max3_f32 v252, v252, v92, v93
	v_max3_f32 v252, v252, v94, v95
	v_max3_f32 v252, v252, v96, v97
	v_max3_f32 v252, v252, v98, v99
	ds_read_b64_tr_b16 v[116:117], v211 offset:0x1200
	ds_read_b64_tr_b16 v[118:119], v211 offset:0x1a00
	v_mfma_f32_32x32x16_bf16 v[32:47], v[104:107], v[120:123], v[32:47]
	v_max3_f32 v252, v252, v68, v69
	v_max3_f32 v252, v252, v70, v71
	v_max3_f32 v252, v252, v72, v73
	v_max3_f32 v252, v252, v74, v75
	v_max3_f32 v252, v252, v76, v77
	ds_read_b64_tr_b16 v[120:121], v211 offset:0x2200
	ds_read_b64_tr_b16 v[122:123], v211 offset:0x2a00
	ds_read_b64_tr_b16 v[178:179], v211 offset:0x3200
	ds_read_b64_tr_b16 v[180:181], v211 offset:0x3a00
	s_waitcnt lgkmcnt(0)
	v_mfma_f32_32x32x16_bf16 v[32:47], v[108:111], v[124:127], v[32:47]
	v_max3_f32 v252, v252, v78, v79
	v_max3_f32 v252, v252, v80, v81
	v_max3_f32 v252, v252, v82, v83
	v_mov_b32_e32 v253, v252
	s_nop 1
	v_mfma_f32_32x32x16_bf16 v[48:63], v[100:103], v[112:115], v[48:63]
	v_permlane32_swap_b32_e32 v252, v253
	v_max_f32_e32 v253, v253, v253
	v_max_f32_e32 v252, v252, v252
	v_max_f32_e32 v252, v252, v253
	v_max_f32_e32 v255, v176, v176
	ds_read_b64_tr_b16 v[112:113], v211 offset:0x400
	ds_read_b64_tr_b16 v[114:115], v211 offset:0xc00
	v_mfma_f32_32x32x16_bf16 v[48:63], v[64:67], v[116:119], v[48:63]
	v_sub_f32_e32 v253, v252, v176
	v_max_f32_e32 v252, v255, v252
	v_sub_f32_e32 v255, v176, v252
	v_mul_f32_e32 v255, 0x3e0293ee, v255
	v_mul_f32_e32 v253, 0x3db504f3, v253
	ds_read_b64_tr_b16 v[116:117], v211 offset:0x1400
	ds_read_b64_tr_b16 v[118:119], v211 offset:0x1c00
	v_mfma_f32_32x32x16_bf16 v[48:63], v[104:107], v[120:123], v[48:63]
	v_exp_f32_e32 v255, v255
	v_cmp_ge_f32_e32 vcc, s82, v253
	s_cmp_eq_u64 vcc, exec
	s_cselect_b64 s[4:5], -1, 0
	ds_read_b64_tr_b16 v[120:121], v211 offset:0x2400
	ds_read_b64_tr_b16 v[122:123], v211 offset:0x2c00
	ds_read_b64_tr_b16 v[124:125], v211 offset:0x3400
	ds_read_b64_tr_b16 v[126:127], v211 offset:0x3c00
	s_waitcnt lgkmcnt(0)
	v_mfma_f32_32x32x16_bf16 v[48:63], v[108:111], v[178:181], v[48:63]
	v_cndmask_b32_e64 v227, v252, v176, s[4:5]
	v_mul_f32_e32 v176, 0xbe0293ee, v227
	v_fmamk_f32 v232, v84, 0x3e0293ee, v176
	v_fmamk_f32 v233, v85, 0x3e0293ee, v176
	v_fmamk_f32 v234, v86, 0x3e0293ee, v176
	v_fmamk_f32 v235, v87, 0x3e0293ee, v176
	v_mfma_f32_32x32x16_bf16 v[16:31], v[100:103], v[112:115], v[16:31]
	v_fmamk_f32 v236, v88, 0x3e0293ee, v176
	v_fmamk_f32 v237, v89, 0x3e0293ee, v176
	v_fmamk_f32 v238, v90, 0x3e0293ee, v176
	v_fmamk_f32 v239, v91, 0x3e0293ee, v176
	v_fmamk_f32 v240, v92, 0x3e0293ee, v176
	v_fmamk_f32 v241, v93, 0x3e0293ee, v176
	ds_read_b64_tr_b16 v[112:113], v211 offset:0x600
	ds_read_b64_tr_b16 v[114:115], v211 offset:0xe00
	v_mfma_f32_32x32x16_bf16 v[16:31], v[64:67], v[116:119], v[16:31]
	v_fmamk_f32 v242, v94, 0x3e0293ee, v176
	v_fmamk_f32 v243, v95, 0x3e0293ee, v176
	v_fmamk_f32 v96, v96, 0x3e0293ee, v176
	v_fmamk_f32 v97, v97, 0x3e0293ee, v176
	v_fmamk_f32 v98, v98, 0x3e0293ee, v176
	v_fmamk_f32 v99, v99, 0x3e0293ee, v176
	ds_read_b64_tr_b16 v[116:117], v211 offset:0x1600
	ds_read_b64_tr_b16 v[118:119], v211 offset:0x1e00
	v_mfma_f32_32x32x16_bf16 v[16:31], v[104:107], v[120:123], v[16:31]
	v_fmamk_f32 v84, v68, 0x3e0293ee, v176
	v_fmamk_f32 v93, v69, 0x3e0293ee, v176
	v_fmamk_f32 v94, v70, 0x3e0293ee, v176
	v_fmamk_f32 v95, v71, 0x3e0293ee, v176
	v_fmamk_f32 v177, v72, 0x3e0293ee, v176
	v_fmamk_f32 v85, v73, 0x3e0293ee, v176
	ds_read_b64_tr_b16 v[120:121], v211 offset:0x2600
	ds_read_b64_tr_b16 v[122:123], v211 offset:0x2e00
	ds_read_b64_tr_b16 v[178:179], v211 offset:0x3600
	ds_read_b64_tr_b16 v[180:181], v211 offset:0x3e00
	s_waitcnt lgkmcnt(0)
	v_mfma_f32_32x32x16_bf16 v[16:31], v[108:111], v[124:127], v[16:31]
	v_fmamk_f32 v86, v74, 0x3e0293ee, v176
	v_fmamk_f32 v87, v75, 0x3e0293ee, v176
	v_fmamk_f32 v88, v76, 0x3e0293ee, v176
	v_fmamk_f32 v89, v77, 0x3e0293ee, v176
	v_fmamk_f32 v90, v78, 0x3e0293ee, v176
	v_fmamk_f32 v91, v79, 0x3e0293ee, v176
	v_mfma_f32_32x32x16_bf16 v[0:15], v[100:103], v[112:115], v[0:15]
	v_exp_f32_e32 v68, v236
	v_exp_f32_e32 v69, v237
	v_exp_f32_e32 v70, v238
	v_exp_f32_e32 v71, v239
	v_exp_f32_e32 v72, v240
	v_exp_f32_e32 v73, v241
	v_mfma_f32_32x32x16_bf16 v[0:15], v[64:67], v[116:119], v[0:15]
	v_exp_f32_e32 v74, v242
	v_exp_f32_e32 v75, v243
	v_exp_f32_e32 v76, v96
	v_exp_f32_e32 v77, v97
	v_exp_f32_e32 v78, v98
	v_exp_f32_e32 v79, v99
	v_exp_f32_e32 v64, v232
	v_exp_f32_e32 v65, v233
	v_exp_f32_e32 v66, v234
	v_exp_f32_e32 v67, v235
	v_mfma_f32_32x32x16_bf16 v[0:15], v[104:107], v[120:123], v[0:15]
	v_fmamk_f32 v92, v80, 0x3e0293ee, v176
	v_mfma_f32_32x32x16_bf16 v[0:15], v[108:111], v[178:181], v[0:15]
	v_fmamk_f32 v178, v81, 0x3e0293ee, v176
	v_fmamk_f32 v179, v82, 0x3e0293ee, v176
	v_fmac_f32_e32 v176, 0x3e0293ee, v83
	s_waitcnt vmcnt(0)
	ds_write_b128 v213, v[168:171] offset:32768
	ds_write_b128 v213, v[172:175] offset:40960
	s_barrier
	s_waitcnt vmcnt(0)
	v_cndmask_b32_e64 v225, v255, 1.0, s[4:5]
	v_cmp_gt_f32_e32 vcc, 1.0, v225
	s_waitcnt vmcnt(3)
	ds_write_b128 v199, v[160:163]
	s_waitcnt vmcnt(2)
	ds_write_b128 v216, v[164:167]
	s_cbranch_vccz .LBB0_221
	s_and_saveexec_b64 s[72:73], s[0:1]
	ds_write_b32 v214, v225 offset:128
	s_or_b64 exec, exec, s[72:73]
	s_waitcnt lgkmcnt(0)
	ds_read_b128 v[100:103], v212 offset:224
	ds_read_b128 v[104:107], v212 offset:192
	ds_read_b128 v[108:111], v212 offset:160
	ds_read_b128 v[112:115], v212 offset:128
	s_waitcnt lgkmcnt(3)
	v_pk_mul_f32 v[46:47], v[46:47], v[102:103]
	s_waitcnt lgkmcnt(2)
	v_pk_mul_f32 v[42:43], v[42:43], v[106:107]
	s_waitcnt lgkmcnt(1)
	v_pk_mul_f32 v[38:39], v[38:39], v[110:111]
	s_waitcnt lgkmcnt(0)
	v_pk_mul_f32 v[34:35], v[34:35], v[114:115]
	v_pk_mul_f32 v[44:45], v[44:45], v[100:101]
	v_pk_mul_f32 v[40:41], v[40:41], v[104:105]
	v_pk_mul_f32 v[36:37], v[36:37], v[108:109]
	v_pk_mul_f32 v[32:33], v[32:33], v[112:113]
	v_pk_mul_f32 v[62:63], v[62:63], v[102:103]
	v_pk_mul_f32 v[58:59], v[58:59], v[106:107]
	v_pk_mul_f32 v[54:55], v[54:55], v[110:111]
	v_pk_mul_f32 v[50:51], v[50:51], v[114:115]
	v_pk_mul_f32 v[60:61], v[60:61], v[100:101]
	v_pk_mul_f32 v[56:57], v[56:57], v[104:105]
	v_pk_mul_f32 v[52:53], v[52:53], v[108:109]
	v_pk_mul_f32 v[48:49], v[48:49], v[112:113]
	v_pk_mul_f32 v[30:31], v[30:31], v[102:103]
	v_pk_mul_f32 v[26:27], v[26:27], v[106:107]
	v_pk_mul_f32 v[22:23], v[22:23], v[110:111]
	v_pk_mul_f32 v[18:19], v[18:19], v[114:115]
	v_pk_mul_f32 v[28:29], v[28:29], v[100:101]
	v_pk_mul_f32 v[24:25], v[24:25], v[104:105]
	v_pk_mul_f32 v[20:21], v[20:21], v[108:109]
	v_pk_mul_f32 v[16:17], v[16:17], v[112:113]
	v_pk_mul_f32 v[14:15], v[14:15], v[102:103]
	v_pk_mul_f32 v[10:11], v[10:11], v[106:107]
	v_pk_mul_f32 v[6:7], v[6:7], v[110:111]
	v_pk_mul_f32 v[2:3], v[2:3], v[114:115]
	v_pk_mul_f32 v[12:13], v[12:13], v[100:101]
	v_pk_mul_f32 v[8:9], v[8:9], v[104:105]
	v_pk_mul_f32 v[4:5], v[4:5], v[108:109]
	v_pk_mul_f32 v[0:1], v[0:1], v[112:113]

.LBB0_225:
	v_mfma_f32_32x32x16_bf16 v[32:47], v[176:179], v[232:235], v[32:47]
	v_max_f32_e32 v252, v113, v113
	v_max_f32_e32 v253, v112, v112
	v_max_f32_e32 v252, v253, v252
	ds_read_b64_tr_b16 v[232:233], v211 offset:0x4200
	ds_read_b64_tr_b16 v[234:235], v211 offset:0x4a00
	v_mfma_f32_32x32x16_bf16 v[32:47], v[180:183], v[236:239], v[32:47]
	v_max3_f32 v252, v252, v114, v115
	v_max3_f32 v252, v252, v116, v117
	v_max3_f32 v252, v252, v118, v119
	ds_read_b64_tr_b16 v[236:237], v211 offset:0x5200
	ds_read_b64_tr_b16 v[238:239], v211 offset:0x5a00
	v_mfma_f32_32x32x16_bf16 v[32:47], v[184:187], v[240:243], v[32:47]
	v_max3_f32 v252, v252, v120, v121
	v_max3_f32 v252, v252, v122, v123
	v_max3_f32 v252, v252, v124, v125
	ds_read_b64_tr_b16 v[240:241], v211 offset:0x6200
	ds_read_b64_tr_b16 v[242:243], v211 offset:0x6a00
	ds_read_b64_tr_b16 v[248:249], v211 offset:0x7200
	ds_read_b64_tr_b16 v[250:251], v211 offset:0x7a00
	s_waitcnt lgkmcnt(0)
	v_mfma_f32_32x32x16_bf16 v[32:47], v[188:191], v[244:247], v[32:47]
	v_max3_f32 v252, v252, v126, v127
	v_max3_f32 v252, v252, v96, v97
	v_max3_f32 v252, v252, v98, v99
	v_mfma_f32_32x32x16_bf16 v[48:63], v[176:179], v[232:235], v[48:63]
	v_max3_f32 v252, v252, v100, v101
	v_max3_f32 v252, v252, v102, v103
	v_max3_f32 v252, v252, v104, v105
	ds_read_b64_tr_b16 v[232:233], v211 offset:0x4400
	ds_read_b64_tr_b16 v[234:235], v211 offset:0x4c00
	v_mfma_f32_32x32x16_bf16 v[48:63], v[180:183], v[236:239], v[48:63]
	v_max3_f32 v252, v252, v106, v107
	v_max3_f32 v252, v252, v108, v109
	v_max3_f32 v252, v252, v110, v111
	ds_read_b64_tr_b16 v[236:237], v211 offset:0x5400
	ds_read_b64_tr_b16 v[238:239], v211 offset:0x5c00
	v_mfma_f32_32x32x16_bf16 v[48:63], v[184:187], v[240:243], v[48:63]
	v_mov_b32_e32 v253, v252
	s_nop 1
	v_permlane32_swap_b32_e32 v252, v253
	ds_read_b64_tr_b16 v[240:241], v211 offset:0x6400
	ds_read_b64_tr_b16 v[242:243], v211 offset:0x6c00
	ds_read_b64_tr_b16 v[244:245], v211 offset:0x7400
	ds_read_b64_tr_b16 v[246:247], v211 offset:0x7c00
	s_waitcnt lgkmcnt(0)
	v_mfma_f32_32x32x16_bf16 v[48:63], v[188:191], v[248:251], v[48:63]
	v_max_f32_e32 v253, v253, v253
	v_max_f32_e32 v252, v252, v252
	v_max_f32_e32 v252, v252, v253
	v_mfma_f32_32x32x16_bf16 v[16:31], v[176:179], v[232:235], v[16:31]
	v_sub_f32_e32 v253, v252, v227
	v_mul_f32_e32 v253, 0x3db504f3, v253
	v_cmp_ge_f32_e32 vcc, s82, v253
	ds_read_b64_tr_b16 v[232:233], v211 offset:0x4600
	ds_read_b64_tr_b16 v[234:235], v211 offset:0x4e00
	v_mfma_f32_32x32x16_bf16 v[16:31], v[180:183], v[236:239], v[16:31]
	s_cmp_eq_u64 vcc, exec
	s_cselect_b64 s[4:5], -1, 0
	ds_read_b64_tr_b16 v[236:237], v211 offset:0x5600
	ds_read_b64_tr_b16 v[238:239], v211 offset:0x5e00
	v_mfma_f32_32x32x16_bf16 v[16:31], v[184:187], v[240:243], v[16:31]
	ds_read_b64_tr_b16 v[240:241], v211 offset:0x6600
	ds_read_b64_tr_b16 v[242:243], v211 offset:0x6e00
	ds_read_b64_tr_b16 v[248:249], v211 offset:0x7600
	ds_read_b64_tr_b16 v[250:251], v211 offset:0x7e00
	s_waitcnt lgkmcnt(0)
	v_mfma_f32_32x32x16_bf16 v[16:31], v[188:191], v[244:247], v[16:31]
	v_mfma_f32_32x32x16_bf16 v[0:15], v[176:179], v[232:235], v[0:15]
	v_mfma_f32_32x32x16_bf16 v[0:15], v[180:183], v[236:239], v[0:15]
	v_mfma_f32_32x32x16_bf16 v[0:15], v[184:187], v[240:243], v[0:15]
	v_mfma_f32_32x32x16_bf16 v[0:15], v[188:191], v[248:251], v[0:15]
	s_andn2_b64 vcc, exec, s[72:73]
	s_cbranch_vccnz .Lkw_skip
	s_waitcnt vmcnt(0)
	ds_write_b128 v213, v[168:171] offset:49152
	ds_write_b128 v213, v[172:175] offset:57344
.Lkw_skip:
	s_andn2_b64 vcc, exec, s[72:73]
	s_barrier
	s_cbranch_vccnz .LBB0_227
	s_waitcnt vmcnt(0)
	s_waitcnt vmcnt(3)
	ds_write_b128 v199, v[160:163] offset:16384
	s_waitcnt vmcnt(2)
	ds_write_b128 v216, v[164:167] offset:16384
